# attention: tile2 step tail without accumulator phi copies; silu(z_attn) epilogue loads issued one step early
# speedup vs baseline: 1.0202x; 1.0202x over previous
; #define LAS __attribute__((address_space(3)))
; __device__ __forceinline__ unsigned pk2(float lo, float hi) { const f32x2c_t v = {lo, hi}; return __builtin_bit_cast(unsigned, __builtin_convertvector(v, bf16x2c_t)); }
; __device__ __forceinline__ float bflo(unsigned w) { return __uint_as_float(w << 16); }
; __device__ __forceinline__ float bfhi(unsigned w) { return __uint_as_float(w & 0xffff0000u); }
; __device__ __forceinline__ int swap23(int r) { return (r & ~12) | ((r & 4) << 1) | ((r & 8) >> 1); }
; __device__ __forceinline__ void phase_attn(const Params& p, LAS unsigned char* lds, unsigned* queue) {
;     const int tid = threadIdx.x, lane = tid & 63, w = __builtin_amdgcn_readfirstlane(tid >> 6), r = lane & 31, hh = lane >> 5;
;     const bf16_t* Qg = (const bf16_t*)(p.ws + WS_Q); const bf16_t* Kg = (const bf16_t*)(p.ws + WS_K); const bf16_t* VTg = (const bf16_t*)(p.ws + WS_VT);
;     const bf16_t* SZA = (const bf16_t*)(p.ws + WS_SZA); const float* KSUM = (const float*)(p.ws + WS_KSUM);
;     bf16_t* MIXED = (bf16_t*)(p.ws + WS_XB);
;     constexpr int ROWB = 144, TILEB = 64 * ROWB, BUFB = 2 * TILEB;
;     const int srow = tid >> 3, sch = tid & 7;
;     const unsigned st_off = (unsigned)(srow * ROWB + sch * 16);
;     const unsigned kf_off = (unsigned)(swap23(r) * ROWB + hh * 16);
;     const unsigned vf_off = (unsigned)(TILEB + r * ROWB + hh * 16);
;     volatile LAS unsigned* tick = (volatile LAS unsigned*)(lds + LDS_CTL + 8);
;     ...
;         lrun += __shfl_xor(lrun, 32);
;         const float inv = 1.f / lrun;
;         const size_t row = (size_t)b * 2048 + qpos;
; #pragma unroll
;         for (int dt = 0; dt < 2; ++dt)
; #pragma unroll
;             for (int g4 = 0; g4 < 4; ++g4) {
;                 const int d0 = 32 * dt + 8 * g4 + 4 * hh;
;                 const u32x2 z2 = *(const u32x2*)(SZA + row * 512 + h * 64 + d0);
;                 float o0, o1, o2, o3;
;                 if (dt == 0) { o0 = O0[4 * g4]; o1 = O0[4 * g4 + 1]; o2 = O0[4 * g4 + 2]; o3 = O0[4 * g4 + 3]; }
;                 else { o0 = O1[4 * g4]; o1 = O1[4 * g4 + 1]; o2 = O1[4 * g4 + 2]; o3 = O1[4 * g4 + 3]; }
;                 o0 *= inv * bflo(z2[0]); o1 *= inv * bfhi(z2[0]); o2 *= inv * bflo(z2[1]); o3 *= inv * bfhi(z2[1]);
;                 *(u32x2*)(MIXED + row * 1024 + h * 64 + d0) = (u32x2){pk2(o0, o1), pk2(o2, o3)};
;             }
.LBB0_330:
	s_add_u32 s0, s78, 0xbd03a00
	s_addc_u32 s1, s79, 0
	v_and_b32_e32 v3, 7, v0
	v_lshlrev_b32_e32 v5, 1, v0
	v_writelane_b32 v255, s0, 6
	v_bfe_u32 v8, v0, 5, 1
	v_lshlrev_b32_e32 v4, 4, v3
	v_and_b32_e32 v3, 19, v0
	v_and_b32_e32 v5, 8, v5
	v_and_b32_e32 v2, 4, v2
	v_writelane_b32 v255, s1, 7
	s_movk_i32 s1, 0x90
	v_or3_b32 v3, v3, v5, v2
	v_lshlrev_b32_e32 v2, 4, v8
	v_mad_u32_u24 v197, v3, s1, v2
	v_mov_b32_e32 v3, 0
	v_readfirstlane_b32 s0, v0
	v_lshlrev_b32_e32 v6, 5, v8
	v_mov_b32_e32 v7, v3
	s_lshr_b32 s3, s0, 1
	v_lshl_add_u64 v[180:181], s[10:11], 0, v[6:7]
	v_lshlrev_b32_e32 v6, 12, v200
	s_and_b32 s3, s3, 0x7fffffe0
	v_mov_b32_e32 v5, v3
	v_lshl_add_u64 v[6:7], s[8:9], 0, v[6:7]
	v_mbcnt_hi_u32_b32 v192, -1, v250
	v_mul_u32_u24_e32 v9, 0x90, v200
	v_or_b32_e32 v199, s3, v212
	v_lshl_add_u64 v[178:179], s[12:13], 0, v[2:3]
	v_lshl_add_u64 v[184:185], v[6:7], 0, v[4:5]
	s_lshr_b32 s3, s0, 7
	v_lshlrev_b32_e32 v6, 2, v8
	v_mad_u32_u24 v205, v212, s1, v2
	s_add_i32 s90, 0, 0x22008
	v_and_b32_e32 v2, 64, v192
	v_lshlrev_b32_e32 v203, 3, v8
	v_lshl_add_u64 v[182:183], s[6:7], 0, v[4:5]
	s_mov_b32 s83, 0
	v_add3_u32 v204, v9, v4, 0
	s_lshl_b32 s88, s3, 6
	s_add_i32 s89, s3, -1
	v_mov_b32_e32 v212, s90
	s_mov_b32 s91, 0x41000000
	v_lshlrev_b32_e32 v186, 1, v6
	v_xor_b32_e32 v193, 32, v192
	v_add_u32_e32 v202, 64, v2
	v_mov_b32_e32 v211, 0xf149f2ca
	s_branch .LBB0_333
.LBB0_331:
	s_waitcnt vmcnt(0)
	s_lshl_b32 s0, s97, 8
	s_and_b32 s0, s0, 0x3800
	v_add_u32_e32 v2, s0, v187
	v_readlane_b32 s0, v255, 4
	v_lshlrev_b64 v[6:7], 10, v[2:3]
	v_readlane_b32 s1, v255, 5
	v_mov_b32_e32 v187, v3
	v_cmp_lt_i32_e32 vcc, v193, v202
	v_lshl_add_u64 v[6:7], s[0:1], 0, v[6:7]
	s_lshl_b32 s0, s96, 7
	s_and_b32 s82, s0, 0x380
	v_lshl_add_u64 v[6:7], v[6:7], 0, s[82:83]
	v_lshl_add_u64 v[6:7], v[6:7], 0, v[186:187]
	v_mov_b64_e32 v[8:9], v[218:219]
	v_mov_b64_e32 v[10:11], v[220:221]
	v_mov_b64_e32 v[12:13], v[222:223]
	v_mov_b64_e32 v[14:15], v[224:225]
	v_mov_b64_e32 v[16:17], v[226:227]
	v_mov_b64_e32 v[18:19], v[228:229]
	v_cndmask_b32_e32 v4, v192, v193, vcc
	v_lshlrev_b32_e32 v4, 2, v4
	ds_bpermute_b32 v4, v4, v5
	v_lshlrev_b64 v[20:21], 11, v[2:3]
	v_readlane_b32 s78, v255, 0
	v_readlane_b32 s79, v255, 1
	s_mov_b64 s[4:5], 0
	s_waitcnt lgkmcnt(0)
	v_add_f32_e32 v2, v5, v4
	v_mov_b64_e32 v[4:5], v[230:231]
	v_div_scale_f32 v22, s[0:1], v2, v2, 1.0
	v_mov_b64_e32 v[6:7], v[232:233]
	v_rcp_f32_e32 v23, v22
	v_div_scale_f32 v24, vcc, 1.0, v2, 1.0
	v_lshl_add_u64 v[20:21], s[78:79], 0, v[20:21]
	v_fma_f32 v25, -v22, v23, 1.0
	v_fmac_f32_e32 v23, v25, v23
	v_mul_f32_e32 v25, v24, v23
	v_fma_f32 v26, -v22, v25, v24
	v_fmac_f32_e32 v25, v26, v23
	v_fma_f32 v22, -v22, v25, v24
	v_div_fmas_f32 v22, v22, v23, v25
	v_div_fixup_f32 v2, v22, v2, 1.0
	v_lshl_add_u64 v[20:21], v[20:21], 0, s[82:83]
	v_lshl_add_u64 v[20:21], v[20:21], 0, v[186:187]
	s_waitcnt vmcnt(7)
	v_lshlrev_b32_e32 v22, 16, v8
	v_and_b32_e32 v23, 0xffff0000, v8
	v_lshlrev_b32_e32 v8, 16, v9
	v_and_b32_e32 v9, 0xffff0000, v9
	s_waitcnt vmcnt(6)
	v_lshlrev_b32_e32 v24, 16, v10
	v_and_b32_e32 v25, 0xffff0000, v10
	v_lshlrev_b32_e32 v10, 16, v11
	v_and_b32_e32 v11, 0xffff0000, v11
	s_waitcnt vmcnt(5)
	v_lshlrev_b32_e32 v26, 16, v12
	v_and_b32_e32 v27, 0xffff0000, v12
	v_lshlrev_b32_e32 v12, 16, v13
	v_and_b32_e32 v13, 0xffff0000, v13
	s_waitcnt vmcnt(4)
	v_lshlrev_b32_e32 v28, 16, v14
	v_and_b32_e32 v29, 0xffff0000, v14
	v_lshlrev_b32_e32 v14, 16, v15
	v_and_b32_e32 v15, 0xffff0000, v15
	v_pk_mul_f32 v[22:23], v[2:3], v[22:23] op_sel_hi:[0,1]
	v_pk_mul_f32 v[8:9], v[2:3], v[8:9] op_sel_hi:[0,1]
	v_pk_mul_f32 v[24:25], v[2:3], v[24:25] op_sel_hi:[0,1]
	v_pk_mul_f32 v[10:11], v[2:3], v[10:11] op_sel_hi:[0,1]
	s_waitcnt vmcnt(3)
	v_lshlrev_b32_e32 v30, 16, v16
	v_and_b32_e32 v31, 0xffff0000, v16
	v_lshlrev_b32_e32 v16, 16, v17
	v_and_b32_e32 v17, 0xffff0000, v17
	v_pk_mul_f32 v[26:27], v[2:3], v[26:27] op_sel_hi:[0,1]
	v_pk_mul_f32 v[12:13], v[2:3], v[12:13] op_sel_hi:[0,1]
	v_pk_mul_f32 v[28:29], v[2:3], v[28:29] op_sel_hi:[0,1]
	v_pk_mul_f32 v[14:15], v[2:3], v[14:15] op_sel_hi:[0,1]
	v_pk_mul_f32 v[22:23], v[98:99], v[22:23]
	v_pk_mul_f32 v[8:9], v[100:101], v[8:9]
	v_pk_mul_f32 v[24:25], v[102:103], v[24:25]
	v_pk_mul_f32 v[10:11], v[104:105], v[10:11]
	v_pk_mul_f32 v[30:31], v[2:3], v[30:31] op_sel_hi:[0,1]
	v_pk_mul_f32 v[16:17], v[2:3], v[16:17] op_sel_hi:[0,1]
	v_pk_mul_f32 v[26:27], v[106:107], v[26:27]
	v_pk_mul_f32 v[12:13], v[108:109], v[12:13]
	v_pk_mul_f32 v[28:29], v[110:111], v[28:29]
	v_pk_mul_f32 v[14:15], v[112:113], v[14:15]
	v_cvt_pk_bf16_f32 v22, v22, v23
	v_cvt_pk_bf16_f32 v23, v8, v9
	v_cvt_pk_bf16_f32 v8, v24, v25
	v_cvt_pk_bf16_f32 v9, v10, v11
	v_pk_mul_f32 v[30:31], v[82:83], v[30:31]
	v_cvt_pk_bf16_f32 v10, v26, v27
	v_cvt_pk_bf16_f32 v11, v12, v13
	v_cvt_pk_bf16_f32 v12, v28, v29
	v_cvt_pk_bf16_f32 v13, v14, v15
	global_store_dwordx2 v[20:21], v[22:23], off
	global_store_dwordx2 v[20:21], v[8:9], off offset:16
	global_store_dwordx2 v[20:21], v[10:11], off offset:32
	global_store_dwordx2 v[20:21], v[12:13], off offset:48
	v_pk_mul_f32 v[8:9], v[84:85], v[16:17]
	v_cvt_pk_bf16_f32 v10, v30, v31
	v_cvt_pk_bf16_f32 v11, v8, v9
	global_store_dwordx2 v[20:21], v[10:11], off offset:64
	s_waitcnt vmcnt(7)
	v_lshlrev_b32_e32 v8, 16, v18
	v_and_b32_e32 v9, 0xffff0000, v18
	v_lshlrev_b32_e32 v10, 16, v19
	v_and_b32_e32 v11, 0xffff0000, v19
	v_pk_mul_f32 v[8:9], v[2:3], v[8:9] op_sel_hi:[0,1]
	v_pk_mul_f32 v[10:11], v[2:3], v[10:11] op_sel_hi:[0,1]
	v_pk_mul_f32 v[8:9], v[86:87], v[8:9]
	v_pk_mul_f32 v[10:11], v[88:89], v[10:11]
	v_cvt_pk_bf16_f32 v8, v8, v9
	v_cvt_pk_bf16_f32 v9, v10, v11
	global_store_dwordx2 v[20:21], v[8:9], off offset:80
	s_waitcnt vmcnt(7)
	v_lshlrev_b32_e32 v8, 16, v4
	v_and_b32_e32 v9, 0xffff0000, v4
	v_lshlrev_b32_e32 v4, 16, v5
	v_and_b32_e32 v5, 0xffff0000, v5
	v_pk_mul_f32 v[8:9], v[2:3], v[8:9] op_sel_hi:[0,1]
	v_pk_mul_f32 v[4:5], v[2:3], v[4:5] op_sel_hi:[0,1]
	v_pk_mul_f32 v[8:9], v[90:91], v[8:9]
	v_pk_mul_f32 v[4:5], v[92:93], v[4:5]
	v_cvt_pk_bf16_f32 v8, v8, v9
	v_cvt_pk_bf16_f32 v9, v4, v5
	s_waitcnt vmcnt(6)
	v_lshlrev_b32_e32 v4, 16, v6
	v_and_b32_e32 v5, 0xffff0000, v6
	v_lshlrev_b32_e32 v6, 16, v7
	v_and_b32_e32 v7, 0xffff0000, v7
	v_pk_mul_f32 v[4:5], v[2:3], v[4:5] op_sel_hi:[0,1]
	v_pk_mul_f32 v[6:7], v[2:3], v[6:7] op_sel_hi:[0,1]
	v_pk_mul_f32 v[4:5], v[94:95], v[4:5]
	v_pk_mul_f32 v[6:7], v[96:97], v[6:7]
	v_cvt_pk_bf16_f32 v4, v4, v5
	v_cvt_pk_bf16_f32 v5, v6, v7
	global_store_dwordx2 v[20:21], v[8:9], off offset:96
	global_store_dwordx2 v[20:21], v[4:5], off offset:112

; __device__ __forceinline__ void phase_attn(const Params& p, LAS unsigned char* lds, unsigned* queue) {
;     ...
;     for (;;) {
;         if (tid == 0) *tick = __hip_atomic_fetch_add(queue, 1u, __ATOMIC_RELAXED, __HIP_MEMORY_SCOPE_AGENT);
;         __syncthreads();
;         const int idx = (int)*tick;
.LBB0_333:
	s_and_saveexec_b64 s[4:5], s[92:93]
	s_cbranch_execz .LBB0_337
	s_mov_b64 s[8:9], exec
	v_mbcnt_lo_u32_b32 v2, s8, 0
	v_mbcnt_hi_u32_b32 v2, s9, v2
	v_cmp_eq_u32_e32 vcc, 0, v2
	s_and_saveexec_b64 s[6:7], vcc
	s_cbranch_execz .LBB0_336
	s_bcnt1_i32_b64 s0, s[8:9]
	v_mov_b32_e32 v4, s0
	v_readlane_b32 s0, v255, 6
	v_readlane_b32 s1, v255, 7
	s_nop 4
	global_atomic_add v4, v3, v4, s[0:1] sc0
.LBB0_336:
	s_or_b64 exec, exec, s[6:7]
	s_waitcnt vmcnt(0)
	v_readfirstlane_b32 s0, v4
	v_mov_b32_e32 v4, s90
	s_nop 0
	v_add_u32_e32 v2, s0, v2
	ds_write_b32 v4, v2

; __device__ __forceinline__ void phase_attn(const Params& p, LAS unsigned char* lds, unsigned* queue) {
;     ...
;         const size_t row = (size_t)b * 2048 + qpos;
; #pragma unroll
;         for (int dt = 0; dt < 2; ++dt)
; #pragma unroll
;             for (int g4 = 0; g4 < 4; ++g4) {
;                 const int d0 = 32 * dt + 8 * g4 + 4 * hh;
;                 const u32x2 z2 = *(const u32x2*)(SZA + row * 512 + h * 64 + d0);
.Lz_prefetch:
	s_lshl_b32 s100, s97, 8
	s_and_b32 s100, s100, 0x3800
	v_add_u32_e32 v234, s100, v187
	v_mov_b32_e32 v235, 0
	v_lshlrev_b64 v[234:235], 10, v[234:235]
	v_readlane_b32 s98, v255, 4
	v_readlane_b32 s99, v255, 5
	v_mov_b32_e32 v236, v186
	v_mov_b32_e32 v237, 0
	s_lshl_b32 s100, s96, 7
	s_and_b32 s100, s100, 0x380
	s_mov_b32 s101, 0
	v_lshl_add_u64 v[234:235], s[98:99], 0, v[234:235]
	v_lshl_add_u64 v[234:235], v[234:235], 0, s[100:101]
	v_lshl_add_u64 v[234:235], v[234:235], 0, v[236:237]
	global_load_dwordx2 v[218:219], v[234:235], off
	global_load_dwordx2 v[220:221], v[234:235], off offset:16
	global_load_dwordx2 v[222:223], v[234:235], off offset:32
	global_load_dwordx2 v[224:225], v[234:235], off offset:48
	global_load_dwordx2 v[226:227], v[234:235], off offset:64
	global_load_dwordx2 v[228:229], v[234:235], off offset:80
	global_load_dwordx2 v[230:231], v[234:235], off offset:96
	global_load_dwordx2 v[232:233], v[234:235], off offset:112
	s_branch .LBB0_385
